# gdn scan producer: chunk advance kept in two scalar base pairs (Z rows / U,WN rows); no per-chunk VALU address work left in the loop
# speedup vs baseline: 1.0070x; 1.0015x over previous
; __device__ __forceinline__ void gdn_scan(const Ctx& c, const Params& p, int e) {
;     ...
;         if (producer) {
;             int pt_ = ptid; asm volatile("" : "+v"(pt_));
;             u32x4 tq[4], tk[4], tw[4], tu[4], tqk[2];
;             const int prow = pt_ >> 4, pc8 = (pt_ & 15) * 8;
;             const int qrow = pt_ >> 3, qc8 = (pt_ & 7) * 8;
;             GDN_LOAD_TILES(0); GDN_STORE_TILES();
.LBB0_530:
	s_and_b64 vcc, exec, s[2:3]
	s_cbranch_vccz .LBB0_521
	s_mul_hi_i32 s2, s20, 0x2aaaaaab
	s_lshr_b32 s3, s2, 31
	s_add_i32 s2, s2, s3
	s_mul_i32 s3, s2, 6
	s_sub_i32 s3, s20, s3
	s_waitcnt vmcnt(0)
	v_mov_b32_e32 v97, v165
	s_lshl_b32 s4, s2, 13
	v_ashrrev_i32_e32 v64, 4, v97
	v_lshlrev_b32_e32 v1, 3, v97
	s_lshl_b32 s2, s3, 7
	s_waitcnt lgkmcnt(0)
	v_and_b32_e32 v12, 0x78, v1
	s_ashr_i32 s5, s4, 31
	v_ashrrev_i32_e32 v65, 31, v64
	s_ashr_i32 s3, s2, 31
	v_lshl_add_u64 v[2:3], v[64:65], 0, s[4:5]
	v_or_b32_e32 v102, s2, v12
	v_mov_b32_e32 v103, s3
	s_movk_i32 s35, 0x300
	v_and_b32_e32 v66, 56, v1
	v_mad_u64_u32 v[6:7], s[20:21], v2, s35, v[102:103]
	v_add_u32_e32 v1, 0x100, v97
	v_mad_i32_i24 v7, v3, s35, v7
	v_mov_b64_e32 v[10:11], s[16:17]
	v_ashrrev_i32_e32 v106, 4, v1
	v_mad_u64_u32 v[4:5], s[20:21], v2, s69, v[10:11]
	v_lshlrev_b64 v[6:7], 1, v[6:7]
	v_ashrrev_i32_e32 v107, 31, v106
	v_mad_i32_i24 v5, v3, s69, v5
	s_lshl_b64 s[20:21], s[2:3], 1
	v_lshlrev_b32_e32 v114, 4, v97
	v_lshl_add_u64 v[68:69], s[8:9], 0, v[6:7]
	v_lshl_add_u64 v[78:79], s[6:7], 0, v[6:7]
	v_lshl_add_u64 v[6:7], v[106:107], 0, s[4:5]
	v_lshl_add_u64 v[8:9], v[4:5], 0, s[20:21]
	v_lshlrev_b32_e32 v104, 1, v12
	v_mov_b32_e32 v105, v0
	v_and_b32_e32 v4, 0x80, v114
	v_mov_b32_e32 v5, v0
	v_mad_u64_u32 v[32:33], s[2:3], v6, s69, v[10:11]
	v_lshl_add_u64 v[14:15], v[8:9], 0, v[104:105]
	v_lshl_add_u64 v[12:13], v[8:9], 0, v[4:5]
	v_lshlrev_b32_e32 v8, 1, v66
	v_mov_b32_e32 v9, v0
	v_mad_i32_i24 v33, v7, s69, v33
	v_lshl_add_u64 v[12:13], v[12:13], 0, v[8:9]
	v_lshl_add_u64 v[32:33], v[32:33], 0, s[20:21]
	global_load_dwordx4 v[16:19], v[14:15], off offset:1536
	global_load_dwordx4 v[20:23], v[12:13], off offset:3072
	v_add_co_u32_e32 v12, vcc, s47, v14
	v_lshl_add_u64 v[32:33], v[32:33], 0, v[4:5]
	s_nop 0
	v_addc_co_u32_e32 v13, vcc, 0, v15, vcc
	v_lshl_add_u64 v[36:37], v[32:33], 0, v[8:9]
	s_movk_i32 s0, 0x6000
	global_load_dwordx4 v[24:27], v[68:69], off
	global_load_dwordx4 v[28:31], v[78:79], off
	global_load_dwordx4 v[32:35], v[12:13], off offset:2048
	s_nop 0
	global_load_dwordx4 v[36:39], v[36:37], off offset:3072
	v_add_co_u32_e32 v12, vcc, s0, v68
	s_mov_b32 s39, 0x3c000
	s_nop 0
	v_addc_co_u32_e32 v13, vcc, 0, v69, vcc
	v_add_co_u32_e32 v44, vcc, s0, v78
	v_add_u32_e32 v94, 0x200, v97
	s_nop 0
	v_addc_co_u32_e32 v45, vcc, 0, v79, vcc
	v_add_co_u32_e32 v48, vcc, s39, v14
	v_add_u32_e32 v95, 0x300, v97
	s_nop 0
	v_addc_co_u32_e32 v49, vcc, 0, v15, vcc
	v_add_co_u32_e32 v56, vcc, s62, v68
	v_ashrrev_i32_e32 v108, 4, v94
	s_nop 0
	v_addc_co_u32_e32 v57, vcc, 0, v69, vcc
	v_add_co_u32_e32 v60, vcc, s62, v78
	s_mov_b32 s42, 0x5a000
	s_nop 0
	v_addc_co_u32_e32 v61, vcc, 0, v79, vcc
	v_ashrrev_i32_e32 v110, 4, v95
	v_ashrrev_i32_e32 v109, 31, v108
	v_add_co_u32_e32 v70, vcc, s42, v14
	v_ashrrev_i32_e32 v111, 31, v110
	global_load_dwordx4 v[40:43], v[12:13], off
	s_nop 0
	global_load_dwordx4 v[44:47], v[44:45], off
	v_lshl_add_u64 v[12:13], v[108:109], 0, s[4:5]
	v_addc_co_u32_e32 v71, vcc, 0, v15, vcc
	v_lshl_add_u64 v[14:15], v[110:111], 0, s[4:5]
	v_mad_u64_u32 v[50:51], s[2:3], v12, s69, v[10:11]
	v_mad_u64_u32 v[72:73], s[2:3], v14, s69, v[10:11]
	v_mad_i32_i24 v51, v13, s69, v51
	v_mad_i32_i24 v73, v15, s69, v73
	v_add_co_u32_e32 v68, vcc, s63, v68
	v_lshl_add_u64 v[50:51], v[50:51], 0, s[20:21]
	v_lshl_add_u64 v[72:73], v[72:73], 0, s[20:21]
	v_addc_co_u32_e32 v69, vcc, 0, v69, vcc
	v_lshl_add_u64 v[50:51], v[50:51], 0, v[4:5]
	v_lshl_add_u64 v[72:73], v[72:73], 0, v[4:5]
	v_add_co_u32_e32 v82, vcc, s63, v78
	v_lshl_add_u64 v[52:53], v[50:51], 0, v[8:9]
	v_lshl_add_u64 v[74:75], v[72:73], 0, v[8:9]
	v_addc_co_u32_e32 v83, vcc, 0, v79, vcc
	global_load_dwordx4 v[48:51], v[48:49], off offset:2560
	s_nop 0
	global_load_dwordx4 v[52:55], v[52:53], off offset:3072
	s_nop 0
	global_load_dwordx4 v[56:59], v[56:57], off
	s_nop 0
	global_load_dwordx4 v[60:63], v[60:61], off
	s_nop 0
	global_load_dwordx4 v[70:73], v[70:71], off offset:3072
	s_nop 0
	global_load_dwordx4 v[74:77], v[74:75], off offset:3072
	s_nop 0
	global_load_dwordx4 v[78:81], v[68:69], off
	s_nop 0
	global_load_dwordx4 v[82:85], v[82:83], off
	v_ashrrev_i32_e32 v68, 3, v97
	v_ashrrev_i32_e32 v69, 31, v68
	v_lshl_add_u64 v[112:113], v[68:69], 0, s[4:5]
	v_mad_u64_u32 v[86:87], s[2:3], v112, s69, v[10:11]
	v_mad_i32_i24 v87, v113, s69, v87
	v_lshl_add_u64 v[86:87], v[86:87], 0, s[20:21]
	v_lshl_add_u64 v[86:87], v[86:87], 0, v[8:9]
	s_movk_i32 s5, 0x1000
	v_add_co_u32_e32 v88, vcc, s5, v86
	s_mov_b32 s44, 0x3d000
	s_nop 0
	v_addc_co_u32_e32 v89, vcc, 0, v87, vcc
	v_add_co_u32_e32 v90, vcc, s44, v86
	v_mul_lo_u32 v67, v64, s36
	s_nop 0
	v_addc_co_u32_e32 v91, vcc, 0, v87, vcc
	global_load_dwordx4 v[86:89], v[88:89], off offset:512
	s_nop 0
	global_load_dwordx4 v[98:101], v[90:91], off offset:1536
	v_add3_u32 v91, s80, v104, v67
	s_waitcnt vmcnt(0) lgkmcnt(0)
	ds_write_b128 v91, v[16:19]
	ds_write_b128 v91, v[24:27] offset:17408
	ds_write_b128 v91, v[28:31] offset:34816
	s_movk_i32 s2, 0x90
	v_lshrrev_b32_e32 v116, 3, v94
	v_add_u32_e32 v96, s80, v8
	v_mul_lo_u32 v116, v116, s2
	v_ashrrev_i32_e32 v1, 3, v1
	v_add_u32_e32 v94, v96, v116
	v_lshrrev_b32_e32 v116, 3, v95
	v_mul_lo_u32 v90, v68, s2
	v_mul_lo_u32 v67, v1, s2
	v_mul_lo_u32 v116, v116, s2
	s_or_b32 s2, s4, 64
	v_add_u32_e32 v95, v96, v116
	v_add_u32_e32 v116, s24, v8
	s_ashr_i32 s3, s2, 31
	v_add_u32_e32 v92, v96, v90
	v_add_u32_e32 v93, v96, v67
	v_add_u32_e32 v96, v116, v90
	v_lshl_add_u64 v[116:117], v[64:65], 0, s[2:3]
	v_mad_u64_u32 v[118:119], s[40:41], v116, s69, v[10:11]
	v_mad_u64_u32 v[120:121], s[40:41], v116, s35, v[102:103]
	v_mad_i32_i24 v119, v117, s69, v119
	v_mad_i32_i24 v121, v117, s35, v121
	v_lshl_add_u64 v[116:117], v[118:119], 0, s[20:21]
	v_lshl_add_u64 v[64:65], v[116:117], 0, v[104:105]
	ds_write_b128 v92, v[20:23] offset:52224
	ds_write_b128 v91, v[32:35] offset:4352
	ds_write_b128 v91, v[40:43] offset:21760
	ds_write_b128 v91, v[44:47] offset:39168
	v_lshlrev_b64 v[120:121], 1, v[120:121]
	v_add_co_u32_e32 v132, vcc, s47, v64
	ds_write_b128 v93, v[36:39] offset:52224
	ds_write_b128 v91, v[48:51] offset:8704
	ds_write_b128 v91, v[56:59] offset:26112
	ds_write_b128 v91, v[60:63] offset:43520
	ds_write_b128 v94, v[52:55] offset:52224
	ds_write_b128 v91, v[70:73] offset:13056
	ds_write_b128 v91, v[78:81] offset:30464
	ds_write_b128 v91, v[82:85] offset:47872
	v_lshl_add_u64 v[224:225], s[8:9], 0, v[120:121]
	v_addc_co_u32_e32 v133, vcc, 0, v65, vcc
	v_add_co_u32_e32 v136, vcc, s0, v224
	v_lshl_add_u64 v[226:227], s[6:7], 0, v[120:121]
	s_nop 0
	v_addc_co_u32_e32 v137, vcc, 0, v225, vcc
	v_add_co_u32_e32 v140, vcc, s0, v226
	v_lshl_add_u64 v[134:135], v[106:107], 0, s[2:3]
	s_nop 0
	v_addc_co_u32_e32 v141, vcc, 0, v227, vcc
	v_add_co_u32_e32 v204, vcc, s39, v64
	v_lshl_add_u64 v[206:207], v[108:109], 0, s[2:3]
	s_nop 0
	v_addc_co_u32_e32 v205, vcc, 0, v65, vcc
	v_add_co_u32_e32 v208, vcc, s62, v224
	v_lshl_add_u64 v[220:221], v[110:111], 0, s[2:3]
	v_mad_u64_u32 v[200:201], s[40:41], v134, s69, v[10:11]
	v_mad_u64_u32 v[216:217], s[40:41], v206, s69, v[10:11]
	v_addc_co_u32_e32 v209, vcc, 0, v225, vcc
	v_mad_u64_u32 v[222:223], s[40:41], v220, s69, v[10:11]
	ds_write_b128 v95, v[74:77] offset:52224
	ds_write_b128 v96, v[86:89]
	ds_write_b128 v96, v[98:101] offset:4608
	v_lshl_add_u64 v[116:117], v[116:117], 0, v[4:5]
	v_mad_i32_i24 v201, v135, s69, v201
	v_mad_i32_i24 v217, v207, s69, v217
	v_add_co_u32_e32 v212, vcc, s62, v226
	v_mad_i32_i24 v223, v221, s69, v223
	v_lshl_add_u64 v[128:129], v[116:117], 0, v[8:9]
	v_lshl_add_u64 v[134:135], v[200:201], 0, s[20:21]
	v_lshl_add_u64 v[206:207], v[216:217], 0, s[20:21]
	v_addc_co_u32_e32 v213, vcc, 0, v227, vcc
	v_lshl_add_u64 v[220:221], v[222:223], 0, s[20:21]
	global_load_dwordx4 v[116:119], v[64:65], off offset:1536
	s_nop 0
	global_load_dwordx4 v[128:131], v[128:129], off offset:3072
	v_lshl_add_u64 v[134:135], v[134:135], 0, v[4:5]
	v_lshl_add_u64 v[206:207], v[206:207], 0, v[4:5]
	v_add_co_u32_e32 v64, vcc, s42, v64
	v_lshl_add_u64 v[220:221], v[220:221], 0, v[4:5]
	v_lshl_add_u64 v[200:201], v[134:135], 0, v[8:9]
	v_lshl_add_u64 v[216:217], v[206:207], 0, v[8:9]
	v_addc_co_u32_e32 v65, vcc, 0, v65, vcc
	v_lshl_add_u64 v[232:233], v[220:221], 0, v[8:9]
	global_load_dwordx4 v[120:123], v[224:225], off
	global_load_dwordx4 v[124:127], v[226:227], off
	s_nop 0
	global_load_dwordx4 v[132:135], v[132:133], off offset:2048
	s_nop 0
	global_load_dwordx4 v[200:203], v[200:201], off offset:3072
	s_nop 0
	global_load_dwordx4 v[136:139], v[136:137], off
	s_nop 0
	global_load_dwordx4 v[140:143], v[140:141], off
	s_nop 0
	global_load_dwordx4 v[204:207], v[204:205], off offset:2560
	s_nop 0
	global_load_dwordx4 v[216:219], v[216:217], off offset:3072
	s_nop 0
	global_load_dwordx4 v[208:211], v[208:209], off
	s_nop 0
	global_load_dwordx4 v[212:215], v[212:213], off
	s_nop 0
	global_load_dwordx4 v[220:223], v[64:65], off offset:3072
	s_nop 0
	global_load_dwordx4 v[232:235], v[232:233], off offset:3072
	v_add_co_u32_e32 v64, vcc, s63, v224
	s_nop 1
	v_addc_co_u32_e32 v65, vcc, 0, v225, vcc
	v_add_co_u32_e32 v228, vcc, s63, v226
	s_nop 1
	v_addc_co_u32_e32 v229, vcc, 0, v227, vcc
	global_load_dwordx4 v[224:227], v[64:65], off
	s_nop 0
	global_load_dwordx4 v[228:231], v[228:229], off
	v_lshl_add_u64 v[64:65], v[68:69], 0, s[2:3]
	v_mad_u64_u32 v[10:11], s[2:3], v64, s69, v[10:11]
	v_mad_i32_i24 v11, v65, s69, v11
	v_lshl_add_u64 v[10:11], v[10:11], 0, s[20:21]
	v_lshl_add_u64 v[10:11], v[10:11], 0, v[8:9]
	v_add_co_u32_e32 v64, vcc, s5, v10
	s_add_u32 s3, s74, s20
	s_nop 0
	v_addc_co_u32_e32 v65, vcc, 0, v11, vcc
	v_add_co_u32_e32 v10, vcc, s44, v10
	s_addc_u32 s5, s75, s21
	s_nop 0
	v_addc_co_u32_e32 v11, vcc, 0, v11, vcc
	global_load_dwordx4 v[236:239], v[64:65], off offset:512
	global_load_dwordx4 v[240:243], v[10:11], off offset:1536
	s_lshl_b32 s35, s34, 1
	s_add_u32 s40, s3, s35
	s_addc_u32 s41, s5, 0
	v_add_u32_e32 v69, s25, v8
	v_lshl_add_u64 v[70:71], s[40:41], 0, v[8:9]
	v_and_b32_e32 v8, 7, v97
	v_lshlrev_b32_e32 v8, 4, v8
	v_mad_u64_u32 v[10:11], s[40:41], v112, s69, v[8:9]
	v_mad_i32_i24 v11, v113, s69, v11
	v_lshl_add_u64 v[76:77], s[22:23], 0, v[10:11]
	v_mad_u64_u32 v[10:11], s[40:41], v14, s69, v[4:5]
	v_mad_i32_i24 v11, v15, s69, v11
	v_lshl_add_u64 v[10:11], v[10:11], 0, v[8:9]
	v_lshl_add_u64 v[78:79], s[18:19], 0, v[10:11]
	v_mad_u64_u32 v[10:11], s[40:41], v12, s69, v[4:5]
	v_mad_i32_i24 v11, v13, s69, v11
	v_lshl_add_u64 v[10:11], v[10:11], 0, v[8:9]
	v_lshl_add_u64 v[80:81], s[18:19], 0, v[10:11]
	v_mad_u64_u32 v[10:11], s[40:41], v6, s69, v[4:5]
	v_mad_i32_i24 v11, v7, s69, v11
	v_mad_u64_u32 v[4:5], s[40:41], v2, s69, v[4:5]
	v_lshl_add_u64 v[6:7], v[10:11], 0, v[8:9]
	v_mad_i32_i24 v5, v3, s69, v5
	v_lshl_add_u64 v[82:83], s[18:19], 0, v[6:7]
	v_and_b32_e32 v6, 0xf0, v114
	v_mov_b32_e32 v7, v0
	v_lshl_add_u64 v[4:5], v[4:5], 0, v[8:9]
	v_mad_u64_u32 v[10:11], s[40:41], v2, s69, v[6:7]
	v_lshl_add_u64 v[86:87], s[18:19], 0, v[4:5]
	v_mad_u64_u32 v[4:5], s[40:41], v2, s50, 0
	v_mad_i32_i24 v11, v3, s69, v11
	v_mad_i32_i24 v3, v3, s50, v5
	v_or_b32_e32 v2, v4, v6
	s_mov_b32 s2, 0
	v_add_u32_e32 v72, s4, v1
	v_add_u32_e32 v74, s4, v68
	v_lshl_add_u64 v[84:85], s[22:23], 0, v[10:11]
	v_lshl_add_u64 v[88:89], s[22:23], 0, v[2:3]
	s_mov_b32 s2, -1
	v_subrev_u32_e32 v72, 64, v72
	v_subrev_u32_e32 v74, 64, v74
	s_mov_b32 s98, 0xff00ff
	s_mov_b32 s99, 0xff00ff00
	s_cmp_eq_u32 s34, 0
	s_cselect_b32 s98, s98, s99
	s_mov_b32 s99, s98
	v_lshl_add_u64 v[50:51], v[84:85], 0, s[20:21]
	v_add_co_u32_e32 v2, vcc, 0x81f1000, v50
	v_lshl_add_u64 v[62:63], v[88:89], 0, s[20:21]
	s_nop 0
	v_addc_co_u32_e32 v3, vcc, 0, v51, vcc
	v_add_co_u32_e32 v10, vcc, 0x1a230000, v62
	s_nop 0
	v_addc_co_u32_e32 v11, vcc, 0, v63, vcc
	v_add_co_u32_e32 v14, vcc, 0x17230000, v62
	v_subrev_u32_e32 v244, s22, v2
	s_nop 0
	v_addc_co_u32_e32 v15, vcc, 0, v63, vcc
	v_add_co_u32_e32 v18, vcc, 0x820f000, v50
	v_subrev_u32_e32 v245, s22, v10
	s_nop 0
	v_addc_co_u32_e32 v19, vcc, 0, v51, vcc
	v_add_co_u32_e32 v26, vcc, 0x1a236000, v62
	v_lshl_add_u64 v[6:7], v[86:87], 0, s[20:21]
	s_nop 0
	v_addc_co_u32_e32 v27, vcc, 0, v63, vcc
	v_add_co_u32_e32 v30, vcc, 0x17236000, v62
	v_subrev_u32_e32 v246, s22, v14
	s_nop 0
	v_addc_co_u32_e32 v31, vcc, 0, v63, vcc
	v_add_co_u32_e32 v34, vcc, 0x822d000, v50
	v_subrev_u32_e32 v247, s22, v6
	s_nop 0
	v_addc_co_u32_e32 v35, vcc, 0, v51, vcc
	v_add_co_u32_e32 v42, vcc, 0x1a23c000, v62
	v_subrev_u32_e32 v248, s22, v18
	s_nop 0
	v_addc_co_u32_e32 v43, vcc, 0, v63, vcc
	v_subrev_u32_e32 v249, s22, v26
	v_add_co_u32_e32 v46, vcc, 0x1723c000, v62
	v_lshl_add_u64 v[22:23], v[82:83], 0, s[20:21]
	v_subrev_u32_e32 v250, s22, v30
	v_addc_co_u32_e32 v47, vcc, 0, v63, vcc
	v_subrev_u32_e32 v251, s22, v22
	v_add_co_u32_e32 v50, vcc, 0x824b000, v50
	v_subrev_u32_e32 v252, s22, v34
	s_nop 0
	v_addc_co_u32_e32 v51, vcc, 0, v51, vcc
	v_subrev_u32_e32 v253, s22, v42
	v_add_co_u32_e32 v58, vcc, 0x1a242000, v62
	v_lshl_add_u64 v[38:39], v[80:81], 0, s[20:21]
	v_subrev_u32_e32 v112, s22, v46
	v_addc_co_u32_e32 v59, vcc, 0, v63, vcc
	v_subrev_u32_e32 v113, s22, v38
	v_add_co_u32_e32 v62, vcc, 0x17242000, v62
	v_subrev_u32_e32 v114, s22, v50
	s_nop 0
	v_addc_co_u32_e32 v63, vcc, 0, v63, vcc
	v_lshl_add_u64 v[102:103], v[76:77], 0, s[20:21]
	v_subrev_u32_e32 v115, s22, v58
	v_add_co_u32_e32 v98, vcc, 0x81f2000, v102
	v_lshl_add_u64 v[54:55], v[78:79], 0, s[20:21]
	v_subrev_u32_e32 v106, s22, v62
	v_addc_co_u32_e32 v99, vcc, 0, v103, vcc
	v_subrev_u32_e32 v107, s22, v54
	v_add_co_u32_e32 v102, vcc, 0x822e000, v102
	v_subrev_u32_e32 v108, s22, v98
	s_nop 0
	v_addc_co_u32_e32 v103, vcc, 0, v103, vcc
	v_subrev_u32_e32 v109, s22, v102
	v_mov_b32_e32 v76, v106
	v_mov_b32_e32 v77, v107
	v_mov_b32_e32 v78, v108
	v_mov_b32_e32 v79, v109
	v_writelane_b32 v150, s20, 0
	v_writelane_b32 v150, s21, 1
	s_mov_b64 s[20:21], s[22:23]
	s_mov_b64 s[40:41], s[22:23]

; #define LDS_BARRIER() do { asm volatile("s_waitcnt lgkmcnt(0)" ::: "memory"); __builtin_amdgcn_s_barrier(); asm volatile("" ::: "memory"); } while (0)
; #define GDN_STORE_O(nn) do { const LAS bf16_t* ob_ = OTb + ((nn) & 1) * 4608; _Pragma("unroll") for (int k_ = 0; k_ < 2; ++k_) { const int vi_ = pt_ + 256 * k_, row_ = vi_ >> 3, c8_ = (vi_ & 7) * 8; \
;             *(u32x4*)(Y + (size_t)(b * T_ + 64 * (nn) + row_) * D_ + 256 + h * 128 + 64 * dvh + c8_) = *(const LAS u32x4*)(ob_ + row_ * 72 + c8_); } } while (0)
; __device__ __forceinline__ void gdn_scan(const Ctx& c, const Params& p, int e) {
;     ...
;             for (int n = 0; n < 128; ++n) {
;                 LDS_BARRIER();
;                 if (n + 1 < 128) GDN_LOAD_TILES(n + 1);
;                 if (n >= 1) GDN_STORE_O(n - 1);
;                 LDS_BARRIER();
;                 if (n + 1 < 128) GDN_STORE_TILES();
.Lgp_e_nost:
	s_cmpk_eq_i32 s2, 0x7d
	s_cbranch_scc1 .Lgp_e_nold
	global_load_dwordx4 v[2:5], v244, s[20:21] offset:1536
	global_load_dwordx4 v[10:13], v245, s[40:41]
	s_mov_b64 exec, s[98:99]
	global_load_dwordx4 v[14:17], v246, s[40:41]
	s_mov_b64 exec, -1
	global_load_dwordx4 v[6:9], v247, s[20:21]
	global_load_dwordx4 v[18:21], v248, s[20:21] offset:2048
	global_load_dwordx4 v[26:29], v249, s[40:41]
	s_mov_b64 exec, s[98:99]
	global_load_dwordx4 v[30:33], v250, s[40:41]
	s_mov_b64 exec, -1
	global_load_dwordx4 v[22:25], v251, s[20:21]
	global_load_dwordx4 v[34:37], v252, s[20:21] offset:2560
	global_load_dwordx4 v[42:45], v253, s[40:41]
	s_mov_b64 exec, s[98:99]
	global_load_dwordx4 v[46:49], v112, s[40:41]
	s_mov_b64 exec, -1
	global_load_dwordx4 v[38:41], v113, s[20:21]
	global_load_dwordx4 v[50:53], v114, s[20:21] offset:3072
	global_load_dwordx4 v[58:61], v115, s[40:41]
	s_mov_b64 exec, s[98:99]
	global_load_dwordx4 v[62:65], v76, s[40:41]
	s_mov_b64 exec, -1
	global_load_dwordx4 v[54:57], v77, s[20:21]
	global_load_dwordx4 v[98:101], v78, s[20:21] offset:512
	global_load_dwordx4 v[102:105], v79, s[20:21] offset:1536
	s_add_u32 s20, s20, 0x78800
	s_addc_u32 s21, s21, 0
	s_add_u32 s40, s40, 0x18000
	s_addc_u32 s41, s41, 0
.Lgp_e_nold:
	s_add_i32 s2, s2, 1
	s_waitcnt lgkmcnt(0)
	s_barrier
	v_add_u32_e32 v72, 64, v72
	v_add_u32_e32 v74, 64, v74
	s_cmpk_eq_i32 s2, 0x7e
	s_cbranch_scc1 .Lgp_e_w0
	s_waitcnt vmcnt(18)
	s_branch .Lgp_e_wr

; #define LDS_BARRIER() do { asm volatile("s_waitcnt lgkmcnt(0)" ::: "memory"); __builtin_amdgcn_s_barrier(); asm volatile("" ::: "memory"); } while (0)
; #define GDN_STORE_O(nn) do { const LAS bf16_t* ob_ = OTb + ((nn) & 1) * 4608; _Pragma("unroll") for (int k_ = 0; k_ < 2; ++k_) { const int vi_ = pt_ + 256 * k_, row_ = vi_ >> 3, c8_ = (vi_ & 7) * 8; \
;             *(u32x4*)(Y + (size_t)(b * T_ + 64 * (nn) + row_) * D_ + 256 + h * 128 + 64 * dvh + c8_) = *(const LAS u32x4*)(ob_ + row_ * 72 + c8_); } } while (0)
; __device__ __forceinline__ void gdn_scan(const Ctx& c, const Params& p, int e) {
;     ...
;             for (int n = 0; n < 128; ++n) {
;                 LDS_BARRIER();
;                 if (n + 1 < 128) GDN_LOAD_TILES(n + 1);
;                 if (n >= 1) GDN_STORE_O(n - 1);
;                 LDS_BARRIER();
;                 if (n + 1 < 128) GDN_STORE_TILES();
;             }
;             LDS_BARRIER();
;             GDN_STORE_O(127);
.Lgp_e_wr:
	ds_write_b128 v91, v[116:119]
	ds_write_b128 v91, v[120:123] offset:17408
	ds_write_b128 v91, v[124:127] offset:34816
	ds_write_b128 v92, v[128:131] offset:52224
	ds_write_b128 v91, v[132:135] offset:4352
	ds_write_b128 v91, v[136:139] offset:21760
	ds_write_b128 v91, v[140:143] offset:39168
	ds_write_b128 v93, v[200:203] offset:52224
	ds_write_b128 v91, v[204:207] offset:8704
	ds_write_b128 v91, v[208:211] offset:26112
	ds_write_b128 v91, v[212:215] offset:43520
	ds_write_b128 v94, v[216:219] offset:52224
	ds_write_b128 v91, v[220:223] offset:13056
	ds_write_b128 v91, v[224:227] offset:30464
	ds_write_b128 v91, v[228:231] offset:47872
	ds_write_b128 v95, v[232:235] offset:52224
	ds_write_b128 v96, v[236:239]
	ds_write_b128 v96, v[240:243] offset:4608
	s_cmpk_eq_i32 s2, 0x7e
	s_cbranch_scc1 .Lgp_done
	s_waitcnt lgkmcnt(0)
	s_barrier
	s_bitcmp1_b32 s2, 0
	s_cselect_b32 s3, 0x2400, 0
	v_add_u32_e32 v73, s3, v69
	v_add_u32_e32 v75, v73, v90
	ds_read_b128 v[106:109], v75
	v_ashrrev_i32_e32 v75, 31, v74
	v_lshlrev_b64 v[110:111], 11, v[74:75]
	v_lshl_add_u64 v[110:111], v[70:71], 0, v[110:111]
	v_add_u32_e32 v73, v73, v67
	s_waitcnt lgkmcnt(0)
	global_store_dwordx4 v[110:111], v[106:109], off offset:512
	ds_read_b128 v[106:109], v73
	v_ashrrev_i32_e32 v73, 31, v72
	v_lshlrev_b64 v[110:111], 11, v[72:73]
	v_lshl_add_u64 v[110:111], v[70:71], 0, v[110:111]
	s_waitcnt lgkmcnt(0)
	global_store_dwordx4 v[110:111], v[106:109], off offset:512
	global_load_dwordx4 v[116:119], v244, s[20:21] offset:1536
	global_load_dwordx4 v[120:123], v245, s[40:41]
	s_mov_b64 exec, s[98:99]
	global_load_dwordx4 v[124:127], v246, s[40:41]
	s_mov_b64 exec, -1
	global_load_dwordx4 v[128:131], v247, s[20:21]
	global_load_dwordx4 v[132:135], v248, s[20:21] offset:2048
	global_load_dwordx4 v[136:139], v249, s[40:41]
	s_mov_b64 exec, s[98:99]
	global_load_dwordx4 v[140:143], v250, s[40:41]
	s_mov_b64 exec, -1
	global_load_dwordx4 v[200:203], v251, s[20:21]
	global_load_dwordx4 v[204:207], v252, s[20:21] offset:2560
	global_load_dwordx4 v[208:211], v253, s[40:41]
	s_mov_b64 exec, s[98:99]
	global_load_dwordx4 v[212:215], v112, s[40:41]
	s_mov_b64 exec, -1
	global_load_dwordx4 v[216:219], v113, s[20:21]
	global_load_dwordx4 v[220:223], v114, s[20:21] offset:3072
	global_load_dwordx4 v[224:227], v115, s[40:41]
	s_mov_b64 exec, s[98:99]
	global_load_dwordx4 v[228:231], v76, s[40:41]
	s_mov_b64 exec, -1
	global_load_dwordx4 v[232:235], v77, s[20:21]
	global_load_dwordx4 v[236:239], v78, s[20:21] offset:512
	global_load_dwordx4 v[240:243], v79, s[20:21] offset:1536
	s_add_u32 s20, s20, 0x78800
	s_addc_u32 s21, s21, 0
	s_add_u32 s40, s40, 0x18000
	s_addc_u32 s41, s41, 0
	s_add_i32 s2, s2, 1
	s_waitcnt lgkmcnt(0)
	s_barrier
	v_add_u32_e32 v72, 64, v72
	v_add_u32_e32 v74, 64, v74
	s_waitcnt vmcnt(18)
	ds_write_b128 v91, v[2:5]
	ds_write_b128 v91, v[10:13] offset:17408
	ds_write_b128 v91, v[14:17] offset:34816
	ds_write_b128 v92, v[6:9] offset:52224
	ds_write_b128 v91, v[18:21] offset:4352
	ds_write_b128 v91, v[26:29] offset:21760
	ds_write_b128 v91, v[30:33] offset:39168
	ds_write_b128 v93, v[22:25] offset:52224
	ds_write_b128 v91, v[34:37] offset:8704
	ds_write_b128 v91, v[42:45] offset:26112
	ds_write_b128 v91, v[46:49] offset:43520
	ds_write_b128 v94, v[38:41] offset:52224
	ds_write_b128 v91, v[50:53] offset:13056
	ds_write_b128 v91, v[58:61] offset:30464
	ds_write_b128 v91, v[62:65] offset:47872
	ds_write_b128 v95, v[54:57] offset:52224
	ds_write_b128 v96, v[98:101]
	ds_write_b128 v96, v[102:105] offset:4608
	s_branch .Lgp_even
.Lgp_done:
	v_readlane_b32 s20, v150, 0
	v_readlane_b32 s21, v150, 1
	s_nop 3
	s_or_b32 s2, s4, 0x1f80
	v_add_u32_e32 v6, s2, v68
	s_waitcnt lgkmcnt(0)
	s_barrier
	v_add_u32_e32 v2, v69, v90
	v_ashrrev_i32_e32 v7, 31, v6
	ds_read_b128 v[2:5], v2
	v_lshlrev_b64 v[6:7], 11, v[6:7]
	v_lshl_add_u64 v[6:7], s[74:75], 0, v[6:7]
	v_lshl_add_u64 v[6:7], v[6:7], 0, s[20:21]
	s_lshl_b32 s42, s34, 1
	v_lshl_add_u64 v[6:7], v[6:7], 0, s[42:43]
	v_lshlrev_b32_e32 v8, 1, v66
	v_mov_b32_e32 v9, v0
	v_lshl_add_u64 v[6:7], v[6:7], 0, v[8:9]
	s_waitcnt lgkmcnt(0)
	global_store_dwordx4 v[6:7], v[2:5], off offset:512
	v_add_u32_e32 v6, s2, v1
	v_ashrrev_i32_e32 v7, 31, v6
	v_add_u32_e32 v2, v69, v67
	ds_read_b128 v[2:5], v2
	v_lshlrev_b64 v[6:7], 11, v[6:7]
	v_lshl_add_u64 v[6:7], s[74:75], 0, v[6:7]
	v_lshl_add_u64 v[6:7], v[6:7], 0, s[20:21]
	v_lshl_add_u64 v[6:7], v[6:7], 0, s[42:43]
	v_lshl_add_u64 v[6:7], v[6:7], 0, v[8:9]
	s_waitcnt lgkmcnt(0)
	global_store_dwordx4 v[6:7], v[2:5], off offset:512
	s_or_b32 s2, s4, 0x1fc0
	s_waitcnt lgkmcnt(0)
	s_barrier
	v_add_u32_e32 v10, s26, v8
	v_add_u32_e32 v6, s2, v68
	s_waitcnt lgkmcnt(0)
	s_barrier
	v_add_u32_e32 v2, v10, v90
	v_ashrrev_i32_e32 v7, 31, v6
	ds_read_b128 v[2:5], v2
	v_lshlrev_b64 v[6:7], 11, v[6:7]
	v_lshl_add_u64 v[6:7], s[74:75], 0, v[6:7]
	v_lshl_add_u64 v[6:7], v[6:7], 0, s[20:21]
	v_lshl_add_u64 v[6:7], v[6:7], 0, s[42:43]
	v_lshl_add_u64 v[6:7], v[6:7], 0, v[8:9]
	s_waitcnt lgkmcnt(0)
	global_store_dwordx4 v[6:7], v[2:5], off offset:512
	v_add_u32_e32 v6, s2, v1
	v_ashrrev_i32_e32 v7, 31, v6
	v_add_u32_e32 v2, v10, v67
	ds_read_b128 v[2:5], v2
	v_lshlrev_b64 v[6:7], 11, v[6:7]
	v_lshl_add_u64 v[6:7], s[74:75], 0, v[6:7]
	v_lshl_add_u64 v[6:7], v[6:7], 0, s[20:21]
	v_lshl_add_u64 v[6:7], v[6:7], 0, s[42:43]
	v_lshl_add_u64 v[6:7], v[6:7], 0, v[8:9]
	v_readlane_b32 s41, v255, 14
	s_waitcnt lgkmcnt(0)
	global_store_dwordx4 v[6:7], v[2:5], off offset:512
	s_branch .LBB0_521
